# S10: SSD diagonal-block causal masks compare k against a per-lane (col - rowpart) difference instead of or-ing a row index per element (15 VALU per 32x32 block dropped, both directions); on top of CON
# baseline (speedup 1.0000x reference)
; #define LAS __attribute__((address_space(3)))
; __device__ __forceinline__ float bflo(unsigned w) { return __uint_as_float(w << 16); }
; __device__ __forceinline__ float bfhi(unsigned w) { return __uint_as_float(w & 0xffff0000u); }
; __device__ __forceinline__ f32x16 mfma32(bf16x8 a, bf16x8 b, f32x16 c) { return __builtin_amdgcn_mfma_f32_32x32x16_bf16(a, b, c, 0, 0, 0); }
;     ...
;                 { const float ec = __expf(ci - mi);
; #pragma unroll
;                   for (int e = 0; e < 16; ++e) Ya[e] *= ec; }
;                 {
;                     const int i = 32 * ib + r; const int jb = ib;
;                     f32x16 S;
;                     { const int bi2 = DIR ? 3 - ib : ib, bj2 = DIR ? 3 - jb : jb; const LAS u32x4* srcp = (const LAS u32x4*)(CBL + (bi2 * (bi2 + 1) / 2 + bj2) * 2048 + lane * 32);
;                       const u32x4 w0 = srcp[0], w1 = srcp[1];
;                       S[0] = bflo(w0.x); S[1] = bfhi(w0.x); S[2] = bflo(w0.y); S[3] = bfhi(w0.y); S[4] = bflo(w0.z); S[5] = bfhi(w0.z); S[6] = bflo(w0.w); S[7] = bfhi(w0.w);
;                       S[8] = bflo(w1.x); S[9] = bfhi(w1.x); S[10] = bflo(w1.y); S[11] = bfhi(w1.y); S[12] = bflo(w1.z); S[13] = bfhi(w1.z); S[14] = bflo(w1.w); S[15] = bfhi(w1.w); }
; #pragma unroll
;                     for (int q = 0; q < 4; ++q) {
;                         const int j0 = 32 * jb + 8 * q + 4 * h;
;                         const f32x4 cj = *(const LAS f32x4*)(cumL + j0), dj = *(const LAS f32x4*)(dtL + j0);
; #pragma unroll
;                         for (int k = 0; k < 4; ++k) {
;                             const int j = j0 + k; const bool valid = DIR ? (j >= i) : (j <= i);
;                             float v = S[4 * q + k] * __expf(ci - cj[k]) * dj[k];
;                             v = valid ? v : 0.f;
;                             if (DIR == 0 && j == i) v += Dh;
;                             S[4 * q + k] = v;
;                         }
;                     }
;                     Ya = mfma32(ld44(XT + 32 * jb + 4 * h), pack_acc(S, 0), Ya); Ya = mfma32(ld44(XT + 32 * jb + 16 + 4 * h), pack_acc(S, 1), Ya);
;                 }
.LBB0_431:
	s_waitcnt lgkmcnt(0)
	v_sub_f32_e32 v80, v89, v80
	v_mul_f32_e32 v80, 0x3fb8aa3b, v80
	v_add_u32_e32 v91, s62, v208
	v_exp_f32_e32 v140, v80
	ds_read_b128 v[80:83], v91
	ds_read_b128 v[144:147], v91 offset:16
	v_or_b32_e32 v226, s69, v116
	v_sub_u32_e32 v173, v99, v116
	v_lshl_add_u32 v227, v226, 2, s76
	s_lshl_b32 s66, s69, 1
	s_waitcnt lgkmcnt(0)
	v_lshlrev_b32_e32 v91, 16, v80
	v_and_b32_e32 v152, 0xffff0000, v80
	v_lshlrev_b32_e32 v153, 16, v81
	v_and_b32_e32 v155, 0xffff0000, v81
	v_lshlrev_b32_e32 v156, 16, v82
	v_and_b32_e32 v157, 0xffff0000, v82
	v_lshlrev_b32_e32 v192, 16, v83
	v_and_b32_e32 v194, 0xffff0000, v83
	ds_read_b128 v[148:151], v227 offset:512
	ds_read_b128 v[216:219], v227
	ds_read_b128 v[80:83], v227 offset:32
	s_waitcnt lgkmcnt(3)
	v_lshlrev_b32_e32 v196, 16, v145
	v_and_b32_e32 v197, 0xffff0000, v145
	v_lshlrev_b32_e32 v225, 16, v147
	s_waitcnt lgkmcnt(0)
	v_sub_f32_e32 v145, v89, v216
	v_mul_f32_e32 v145, 0x3fb8aa3b, v145
	v_exp_f32_e32 v145, v145
	v_and_b32_e32 v154, 0xffff0000, v147
	s_waitcnt lgkmcnt(0)
	v_sub_f32_e32 v80, v89, v80
	v_mul_f32_e32 v80, 0x3fb8aa3b, v80
	v_mul_f32_e32 v91, v145, v91
	v_sub_f32_e32 v145, v89, v217
	v_mul_f32_e32 v145, 0x3fb8aa3b, v145
	v_exp_f32_e32 v145, v145
	v_mul_f32_e32 v91, v148, v91
	v_cndmask_b32_e64 v147, v91, 0, s[14:15]
	v_mul_f32_e32 v145, v145, v152
	v_mul_f32_e32 v145, v149, v145
	v_cmp_ge_i32_e32 vcc, 1, v173
	v_sub_f32_e32 v81, v89, v81
	v_cndmask_b32_e32 v148, 0, v145, vcc
	v_sub_f32_e32 v145, v89, v218
	v_mul_f32_e32 v145, 0x3fb8aa3b, v145
	v_exp_f32_e32 v145, v145
	v_cmp_ge_i32_e32 vcc, 2, v173
	v_sub_f32_e32 v82, v89, v82
	v_sub_f32_e32 v83, v89, v83
	v_mul_f32_e32 v145, v145, v153
	v_mul_f32_e32 v145, v150, v145
	v_cndmask_b32_e32 v149, 0, v145, vcc
	v_sub_f32_e32 v145, v89, v219
	v_mul_f32_e32 v145, 0x3fb8aa3b, v145
	v_exp_f32_e32 v145, v145
	ds_read_b128 v[216:219], v227 offset:544
	v_exp_f32_e32 v80, v80
	v_mul_f32_e32 v81, 0x3fb8aa3b, v81
	v_mul_f32_e32 v82, 0x3fb8aa3b, v82
	v_mul_f32_e32 v83, 0x3fb8aa3b, v83
	v_exp_f32_e32 v81, v81
	v_exp_f32_e32 v82, v82
	v_exp_f32_e32 v83, v83
	v_mul_f32_e32 v145, v145, v155
	v_mul_f32_e32 v145, v151, v145
	v_cmp_ge_i32_e32 vcc, 3, v173
	v_mul_f32_e32 v80, v80, v156
	v_cndmask_b32_e32 v150, 0, v145, vcc
	s_waitcnt lgkmcnt(0)
	v_mul_f32_e32 v80, v216, v80
	v_cmp_ge_i32_e32 vcc, 8, v173
	v_mul_f32_e32 v81, v81, v157
	v_mul_f32_e32 v82, v82, v192
	v_mul_f32_e32 v83, v83, v194
	v_cndmask_b32_e32 v80, 0, v80, vcc
	v_mul_f32_e32 v81, v217, v81
	v_cmp_ge_i32_e32 vcc, 9, v173
	v_mul_f32_e32 v82, v218, v82
	v_mul_f32_e32 v83, v219, v83
	ds_read_b128 v[216:219], v227 offset:64
	ds_read_b128 v[220:223], v227 offset:576
	v_cndmask_b32_e32 v81, 0, v81, vcc
	v_cmp_ge_i32_e32 vcc, 10, v173
	v_lshlrev_b32_e32 v195, 16, v144
	v_and_b32_e32 v144, 0xffff0000, v144
	v_cndmask_b32_e32 v192, 0, v82, vcc
	v_cmp_ge_i32_e32 vcc, 11, v173
	v_lshlrev_b32_e32 v215, 16, v146
	v_cndmask_b32_e32 v194, 0, v83, vcc
	s_waitcnt lgkmcnt(0)
	v_sub_f32_e32 v83, v89, v216
	v_mul_f32_e32 v83, 0x3fb8aa3b, v83
	v_exp_f32_e32 v83, v83
	v_cmp_ge_i32_e32 vcc, 16, v173
	v_and_b32_e32 v224, 0xffff0000, v146
	v_mul_f32_e32 v83, v83, v195
	s_waitcnt lgkmcnt(0)
	v_mul_f32_e32 v83, v220, v83
	v_cndmask_b32_e32 v91, 0, v83, vcc
	v_sub_f32_e32 v83, v89, v217
	v_mul_f32_e32 v83, 0x3fb8aa3b, v83
	v_exp_f32_e32 v83, v83
	v_cmp_ge_i32_e32 vcc, 17, v173
	v_pk_mul_f32 v[78:79], v[140:141], v[78:79] op_sel_hi:[0,1]
	v_mul_f32_e32 v83, v83, v144
	v_mul_f32_e32 v83, v221, v83
	v_cndmask_b32_e32 v144, 0, v83, vcc
	v_sub_f32_e32 v83, v89, v218
	v_mul_f32_e32 v83, 0x3fb8aa3b, v83
	v_exp_f32_e32 v83, v83
	v_cmp_ge_i32_e32 vcc, 18, v173
	v_pk_mul_f32 v[76:77], v[140:141], v[76:77] op_sel_hi:[0,1]
	v_mul_f32_e32 v83, v83, v196
	v_mul_f32_e32 v83, v222, v83
	v_cndmask_b32_e32 v145, 0, v83, vcc
	v_sub_f32_e32 v83, v89, v219
	v_mul_f32_e32 v83, 0x3fb8aa3b, v83
	v_exp_f32_e32 v83, v83
	v_cmp_ge_i32_e32 vcc, 19, v173
	v_pk_mul_f32 v[74:75], v[140:141], v[74:75] op_sel_hi:[0,1]
	v_mul_f32_e32 v83, v83, v197
	v_mul_f32_e32 v83, v223, v83
	ds_read_b128 v[216:219], v227 offset:96
	ds_read_b128 v[220:223], v227 offset:608
	v_cndmask_b32_e32 v146, 0, v83, vcc
	v_cmp_ge_i32_e32 vcc, 24, v173
	s_waitcnt lgkmcnt(0)
	v_sub_f32_e32 v83, v89, v216
	v_mul_f32_e32 v83, 0x3fb8aa3b, v83
	v_exp_f32_e32 v83, v83
	v_pk_mul_f32 v[72:73], v[140:141], v[72:73] op_sel_hi:[0,1]
	v_pk_mul_f32 v[70:71], v[140:141], v[70:71] op_sel_hi:[0,1]
	v_pk_mul_f32 v[68:69], v[140:141], v[68:69] op_sel_hi:[0,1]
	v_mul_f32_e32 v83, v83, v215
	s_waitcnt lgkmcnt(0)
	v_mul_f32_e32 v83, v220, v83
	v_cndmask_b32_e32 v151, 0, v83, vcc
	v_sub_f32_e32 v83, v89, v217
	v_mul_f32_e32 v83, 0x3fb8aa3b, v83
	v_exp_f32_e32 v83, v83
	v_cmp_ge_i32_e32 vcc, 25, v173
	v_pk_mul_f32 v[66:67], v[140:141], v[66:67] op_sel_hi:[0,1]
	v_mul_f32_e32 v83, v83, v224
	v_mul_f32_e32 v83, v221, v83
	v_cndmask_b32_e32 v152, 0, v83, vcc
	v_sub_f32_e32 v83, v89, v218
	v_mul_f32_e32 v83, 0x3fb8aa3b, v83
	v_exp_f32_e32 v83, v83
	v_cmp_ge_i32_e32 vcc, 26, v173
	v_pk_mul_f32 v[64:65], v[140:141], v[64:65] op_sel_hi:[0,1]
	v_mul_f32_e32 v83, v83, v225
	v_mul_f32_e32 v83, v222, v83
	v_cndmask_b32_e32 v153, 0, v83, vcc
	v_sub_f32_e32 v83, v89, v219
	v_mul_f32_e32 v83, 0x3fb8aa3b, v83
	v_exp_f32_e32 v83, v83
	v_cmp_ge_i32_e32 vcc, 27, v173
	s_add_i32 s97, s97, 1
	s_add_i32 s83, s83, -1
	v_mul_f32_e32 v83, v83, v154
	v_mul_f32_e32 v83, v223, v83
	v_cndmask_b32_e32 v89, 0, v83, vcc
	s_cmp_eq_u32 s97, 1
	s_cbranch_scc1 .Lssd_a_dg_0
	s_cmp_eq_u32 s97, 2
	s_cbranch_scc1 .Lssd_a_dg_1
	s_cmp_eq_u32 s97, 3
	s_cbranch_scc1 .Lssd_a_dg_2
	v_mov_b32_e32 v154, v228
	v_mov_b32_e32 v155, v229
	v_mov_b32_e32 v156, v230
	v_mov_b32_e32 v157, v231
	v_mov_b32_e32 v248, v232
	v_mov_b32_e32 v249, v233
	v_mov_b32_e32 v250, v234
	v_mov_b32_e32 v251, v235
	s_branch .Lssd_a_dg_done

; #define LAS __attribute__((address_space(3)))
; __device__ __forceinline__ float bflo(unsigned w) { return __uint_as_float(w << 16); }
; __device__ __forceinline__ float bfhi(unsigned w) { return __uint_as_float(w & 0xffff0000u); }
; __device__ __forceinline__ f32x16 mfma32(bf16x8 a, bf16x8 b, f32x16 c) { return __builtin_amdgcn_mfma_f32_32x32x16_bf16(a, b, c, 0, 0, 0); }
;     ...
;                 {
;                     const int i = 32 * ib + r; const int jb = ib;
;                     f32x16 S;
;                     { const int bi2 = DIR ? 3 - ib : ib, bj2 = DIR ? 3 - jb : jb; const LAS u32x4* srcp = (const LAS u32x4*)(CBL + (bi2 * (bi2 + 1) / 2 + bj2) * 2048 + lane * 32);
;                       const u32x4 w0 = srcp[0], w1 = srcp[1];
;                       S[0] = bflo(w0.x); S[1] = bfhi(w0.x); S[2] = bflo(w0.y); S[3] = bfhi(w0.y); S[4] = bflo(w0.z); S[5] = bfhi(w0.z); S[6] = bflo(w0.w); S[7] = bfhi(w0.w);
;                       S[8] = bflo(w1.x); S[9] = bfhi(w1.x); S[10] = bflo(w1.y); S[11] = bfhi(w1.y); S[12] = bflo(w1.z); S[13] = bfhi(w1.z); S[14] = bflo(w1.w); S[15] = bfhi(w1.w); }
; #pragma unroll
;                     for (int q = 0; q < 4; ++q) {
;                         const int j0 = 32 * jb + 8 * q + 4 * h;
;                         const f32x4 cj = *(const LAS f32x4*)(cumL + j0), dj = *(const LAS f32x4*)(dtL + j0);
; #pragma unroll
;                         for (int k = 0; k < 4; ++k) {
;                             const int j = j0 + k; const bool valid = DIR ? (j >= i) : (j <= i);
;                             float v = S[4 * q + k] * __expf(ci - cj[k]) * dj[k];
;                             v = valid ? v : 0.f;
;                             if (DIR == 0 && j == i) v += Dh;
;                             S[4 * q + k] = v;
;                         }
;                     }
;                     Ya = mfma32(ld44(XT + 32 * jb + 4 * h), pack_acc(S, 0), Ya); Ya = mfma32(ld44(XT + 32 * jb + 16 + 4 * h), pack_acc(S, 1), Ya);
;                 }
.LBB0_453:
	s_waitcnt lgkmcnt(0)
	v_sub_f32_e32 v80, v139, v141
	s_add_i32 s63, s64, s66
	v_mul_f32_e32 v80, 0x3fb8aa3b, v80
	v_lshl_add_u32 v85, s63, 11, v208
	v_exp_f32_e32 v84, v80
	ds_read_b128 v[80:83], v85
	ds_read_b128 v[86:89], v85 offset:16
	v_or_b32_e32 v156, s59, v116
	v_sub_u32_e32 v173, v99, v116
	v_lshl_add_u32 v157, v156, 2, s76
	s_lshl_b32 s66, s59, 1
	s_waitcnt lgkmcnt(0)
	v_lshlrev_b32_e32 v85, 16, v80
	v_and_b32_e32 v192, 0xffff0000, v80
	v_lshlrev_b32_e32 v194, 16, v81
	v_and_b32_e32 v195, 0xffff0000, v81
	v_lshlrev_b32_e32 v196, 16, v82
	v_and_b32_e32 v197, 0xffff0000, v82
	v_lshlrev_b32_e32 v219, 16, v83
	v_and_b32_e32 v224, 0xffff0000, v83
	s_waitcnt lgkmcnt(0)
	v_lshlrev_b32_e32 v228, 16, v86
	v_and_b32_e32 v90, 0xffff0000, v86
	v_lshlrev_b32_e32 v91, 16, v87
	v_and_b32_e32 v92, 0xffff0000, v87
	v_lshlrev_b32_e32 v93, 16, v88
	v_and_b32_e32 v94, 0xffff0000, v88
	v_lshlrev_b32_e32 v95, 16, v89
	v_and_b32_e32 v141, 0xffff0000, v89
	ds_read_b128 v[86:89], v157 offset:512
	ds_read_b128 v[220:223], v157
	ds_read_b128 v[80:83], v157 offset:32
	s_add_i32 s59, s58, 2
	s_add_i32 s55, s55, s58
	v_add_u32_e32 v135, 0x200, v135
	s_waitcnt lgkmcnt(0)
	v_sub_f32_e32 v220, v139, v220
	v_mul_f32_e32 v220, 0x3fb8aa3b, v220
	v_exp_f32_e32 v220, v220
	s_waitcnt lgkmcnt(0)
	v_sub_f32_e32 v80, v139, v80
	v_sub_f32_e32 v81, v139, v81
	v_sub_f32_e32 v82, v139, v82
	v_mul_f32_e32 v85, v220, v85
	v_sub_f32_e32 v220, v139, v221
	v_mul_f32_e32 v220, 0x3fb8aa3b, v220
	v_exp_f32_e32 v220, v220
	v_mul_f32_e32 v85, v86, v85
	v_cndmask_b32_e64 v85, v85, 0, s[26:27]
	v_add_f32_e32 v86, v216, v85
	v_mul_f32_e32 v192, v220, v192
	v_mul_f32_e32 v87, v87, v192
	v_sub_f32_e32 v192, v139, v222
	v_mul_f32_e32 v192, 0x3fb8aa3b, v192
	v_exp_f32_e32 v192, v192
	v_cndmask_b32_e64 v85, v85, v86, s[28:29]
	v_cndmask_b32_e64 v87, 0, v87, s[14:15]
	v_mul_f32_e32 v192, v192, v194
	v_mul_f32_e32 v88, v88, v192
	v_sub_f32_e32 v192, v139, v223
	v_cmp_eq_i32_e32 vcc, 1, v173
	v_add_f32_e32 v86, v216, v87
	v_mul_f32_e32 v192, 0x3fb8aa3b, v192
	v_cndmask_b32_e32 v86, v87, v86, vcc
	v_exp_f32_e32 v192, v192
	v_sub_f32_e32 v83, v139, v83
	v_cmp_le_i32_e32 vcc, 2, v173
	v_mul_f32_e32 v80, 0x3fb8aa3b, v80
	v_mul_f32_e32 v81, 0x3fb8aa3b, v81
	v_mul_f32_e32 v82, 0x3fb8aa3b, v82
	v_mul_f32_e32 v83, 0x3fb8aa3b, v83
	v_cndmask_b32_e32 v88, 0, v88, vcc
	ds_read_b128 v[220:223], v157 offset:544
	v_exp_f32_e32 v80, v80
	v_exp_f32_e32 v81, v81
	v_exp_f32_e32 v82, v82
	v_exp_f32_e32 v83, v83
	v_cmp_eq_i32_e32 vcc, 2, v173
	v_add_f32_e32 v87, v216, v88
	v_mul_f32_e32 v192, v192, v195
	v_cndmask_b32_e32 v87, v88, v87, vcc
	v_mul_f32_e32 v89, v89, v192
	v_cmp_le_i32_e32 vcc, 3, v173
	v_mul_f32_e32 v80, v80, v196
	v_mul_f32_e32 v81, v81, v197
	v_cndmask_b32_e32 v89, 0, v89, vcc
	v_mul_f32_e32 v82, v82, v219
	v_mul_f32_e32 v83, v83, v224
	v_cmp_eq_i32_e32 vcc, 3, v173
	v_add_f32_e32 v88, v216, v89
	s_waitcnt lgkmcnt(0)
	v_mul_f32_e32 v80, v220, v80
	v_mul_f32_e32 v81, v221, v81
	v_mul_f32_e32 v82, v222, v82
	v_mul_f32_e32 v83, v223, v83
	ds_read_b128 v[220:223], v157 offset:64
	ds_read_b128 v[224:227], v157 offset:576
	v_cndmask_b32_e32 v88, v89, v88, vcc
	v_cmp_le_i32_e32 vcc, 8, v173
	s_waitcnt lgkmcnt(0)
	v_sub_f32_e32 v194, v139, v221
	v_mul_f32_e32 v194, 0x3fb8aa3b, v194
	v_cndmask_b32_e32 v80, 0, v80, vcc
	v_cmp_eq_i32_e32 vcc, 8, v173
	v_add_f32_e32 v89, v216, v80
	v_exp_f32_e32 v194, v194
	v_cndmask_b32_e32 v80, v80, v89, vcc
	v_cmp_le_i32_e32 vcc, 9, v173
	v_mul_f32_e32 v90, v194, v90
	v_sub_f32_e32 v194, v139, v222
	v_cndmask_b32_e32 v81, 0, v81, vcc
	v_cmp_eq_i32_e32 vcc, 9, v173
	v_add_f32_e32 v89, v216, v81
	v_sub_f32_e32 v192, v139, v220
	v_cndmask_b32_e32 v81, v81, v89, vcc
	v_cmp_le_i32_e32 vcc, 10, v173
	v_mul_f32_e32 v194, 0x3fb8aa3b, v194
	v_mul_f32_e32 v192, 0x3fb8aa3b, v192
	v_cndmask_b32_e32 v82, 0, v82, vcc
	v_cmp_eq_i32_e32 vcc, 10, v173
	v_add_f32_e32 v89, v216, v82
	v_exp_f32_e32 v194, v194
	v_cndmask_b32_e32 v82, v82, v89, vcc
	v_exp_f32_e32 v192, v192
	v_cmp_le_i32_e32 vcc, 11, v173
	v_mul_f32_e32 v91, v194, v91
	v_sub_f32_e32 v194, v139, v223
	v_cndmask_b32_e32 v83, 0, v83, vcc
	v_cmp_eq_i32_e32 vcc, 11, v173
	v_add_f32_e32 v89, v216, v83
	v_mul_f32_e32 v192, v192, v228
	v_cndmask_b32_e32 v83, v83, v89, vcc
	v_mul_f32_e32 v194, 0x3fb8aa3b, v194
	s_waitcnt lgkmcnt(0)
	v_mul_f32_e32 v192, v224, v192
	v_cmp_le_i32_e32 vcc, 16, v173
	v_exp_f32_e32 v194, v194
	v_mul_f32_e32 v90, v225, v90
	v_cndmask_b32_e32 v192, 0, v192, vcc
	v_cmp_eq_i32_e32 vcc, 16, v173
	v_add_f32_e32 v89, v216, v192
	v_mul_f32_e32 v92, v194, v92
	v_cndmask_b32_e32 v89, v192, v89, vcc
	v_cmp_le_i32_e32 vcc, 17, v173
	v_mul_f32_e32 v91, v226, v91
	v_mul_f32_e32 v92, v227, v92
	v_cndmask_b32_e32 v90, 0, v90, vcc
	ds_read_b128 v[220:223], v157 offset:96
	ds_read_b128 v[224:227], v157 offset:608
	v_cmp_eq_i32_e32 vcc, 17, v173
	v_add_f32_e32 v192, v216, v90
	v_pk_mul_f32 v[78:79], v[84:85], v[78:79] op_sel_hi:[0,1]
	v_cndmask_b32_e32 v90, v90, v192, vcc
	v_cmp_le_i32_e32 vcc, 18, v173
	s_waitcnt lgkmcnt(0)
	v_sub_f32_e32 v157, v139, v220
	v_mul_f32_e32 v157, 0x3fb8aa3b, v157
	v_cndmask_b32_e32 v91, 0, v91, vcc
	v_cmp_eq_i32_e32 vcc, 18, v173
	v_add_f32_e32 v192, v216, v91
	v_exp_f32_e32 v157, v157
	v_cndmask_b32_e32 v91, v91, v192, vcc
	v_cmp_le_i32_e32 vcc, 19, v173
	v_mul_f32_e32 v93, v157, v93
	s_waitcnt lgkmcnt(0)
	v_mul_f32_e32 v93, v224, v93
	v_cndmask_b32_e32 v92, 0, v92, vcc
	v_cmp_eq_i32_e32 vcc, 19, v173
	v_add_f32_e32 v192, v216, v92
	v_pk_mul_f32 v[76:77], v[84:85], v[76:77] op_sel_hi:[0,1]
	v_cndmask_b32_e32 v92, v92, v192, vcc
	v_cmp_le_i32_e32 vcc, 24, v173
	v_pk_mul_f32 v[74:75], v[84:85], v[74:75] op_sel_hi:[0,1]
	v_pk_mul_f32 v[72:73], v[84:85], v[72:73] op_sel_hi:[0,1]
	v_cndmask_b32_e32 v93, 0, v93, vcc
	v_cmp_eq_i32_e32 vcc, 24, v173
	v_sub_f32_e32 v192, v139, v221
	v_mul_f32_e32 v192, 0x3fb8aa3b, v192
	v_exp_f32_e32 v192, v192
	v_add_f32_e32 v157, v216, v93
	v_cndmask_b32_e32 v93, v93, v157, vcc
	v_mul_f32_e32 v94, v192, v94
	v_sub_f32_e32 v192, v139, v222
	v_mul_f32_e32 v192, 0x3fb8aa3b, v192
	v_exp_f32_e32 v192, v192
	v_mul_f32_e32 v94, v225, v94
	v_cmp_le_i32_e32 vcc, 25, v173
	v_sub_f32_e32 v139, v139, v223
	v_mul_f32_e32 v139, 0x3fb8aa3b, v139
	v_cndmask_b32_e32 v94, 0, v94, vcc
	v_cmp_eq_i32_e32 vcc, 25, v173
	v_add_f32_e32 v157, v216, v94
	v_exp_f32_e32 v139, v139
	v_cndmask_b32_e32 v94, v94, v157, vcc
	v_mul_f32_e32 v95, v192, v95
	v_mul_f32_e32 v95, v226, v95
	v_cmp_le_i32_e32 vcc, 26, v173
	v_mul_f32_e32 v139, v139, v141
	v_cndmask_b32_e32 v95, 0, v95, vcc
	v_cmp_eq_i32_e32 vcc, 26, v173
	v_add_f32_e32 v157, v216, v95
	v_mul_f32_e32 v139, v227, v139
	v_cndmask_b32_e32 v95, v95, v157, vcc
	v_cmp_le_i32_e32 vcc, 27, v173
	v_pk_mul_f32 v[70:71], v[84:85], v[70:71] op_sel_hi:[0,1]
	v_pk_mul_f32 v[68:69], v[84:85], v[68:69] op_sel_hi:[0,1]
	v_cndmask_b32_e32 v139, 0, v139, vcc
	v_cmp_eq_i32_e32 vcc, 27, v173
	s_cmp_eq_u32 s66, 0
	s_cbranch_scc1 .Lssd_b_dg_0
; __device__ __forceinline__ f32x16 mfma32(bf16x8 a, bf16x8 b, f32x16 c) { return __builtin_amdgcn_mfma_f32_32x32x16_bf16(a, b, c, 0, 0, 0); }
;     ...
;                     Ya = mfma32(ld44(XT + 32 * jb + 4 * h), pack_acc(S, 0), Ya); Ya = mfma32(ld44(XT + 32 * jb + 16 + 4 * h), pack_acc(S, 1), Ya);
;                 }
	s_cmp_eq_u32 s66, 64
	s_cbranch_scc1 .Lssd_b_dg_1
	s_cmp_eq_u32 s66, 128
	s_cbranch_scc1 .Lssd_b_dg_2
	v_mov_b32_e32 v220, v158
	v_mov_b32_e32 v221, v159
	v_mov_b32_e32 v222, v110
	v_mov_b32_e32 v223, v111
	v_mov_b32_e32 v128, v118
	v_mov_b32_e32 v129, v119
	v_mov_b32_e32 v130, v174
	v_mov_b32_e32 v131, v175
	s_branch .Lssd_b_dg_done
